# attention: workgroups 0-15 run their context unit before their latent unit
# speedup vs baseline: 1.0046x; 1.0046x over previous
; #define LAS __attribute__((address_space(3)))
; __device__ __forceinline__ void attn_mfma(LAS unsigned char* lds, int layer, int G, const int wave_s) {
;     ...
;     const bf16_t* Q = (const bf16_t*)(ws + WS_Q); const bf16_t* Kb = (const bf16_t*)(ws + WS_K); const bf16_t* Vb = (const bf16_t*)(ws + WS_V);
;     bf16_t* YM = (bf16_t*)(ws + WS_YM); const float* ZT = (const float*)(ws + WS_SSHY);
;     const float* gat = Pp->in[20] + layer * ATTW; const float* ghy = Pp->in[19] + layer * HY;
;     const int r32 = lane & 31, hi = lane >> 5, h = wave, kv = h >> 2;
;     const float sk = Pp->in[18][layer * NH + h] * LOG2E;
;     const unsigned lbase = (unsigned)(uintptr_t)lds;
;     LAS float* al_l = (LAS float*)(lds + AT_SCR) + wave * 64; LAS float* li_l = al_l + 32;
;     LAS float* xa = (LAS float*)(lds + AT_XA); LAS float* xh = (LAS float*)(lds + AT_XH);
;     const int nunits = layer == DEPTH - 1 ? ML / 32 : MT / 32;
;     for (int unit = blockIdx.x; unit < nunits; unit += G) {
.LBB0_785:
	s_andn2_b64 vcc, exec, s[36:37]
	s_cbranch_vccnz .LBB0_884
	s_cmp_lg_u32 s76, 3
	s_cselect_b64 s[44:45], -1, 0
	s_and_b64 s[0:1], s[44:45], exec
	s_movk_i32 s0, 0x110
	s_cselect_b32 s0, s0, 0x100
	s_cmp_ge_i32 s2, s0
	v_readlane_b32 s17, v253, 2
	s_mov_b64 s[36:37], s[94:95]
	v_mbcnt_lo_u32_b32 v0, -1, 0
	v_mbcnt_hi_u32_b32 v0, -1, v0
	s_cbranch_scc1 .LBB0_826
	s_load_dwordx2 s[40:41], s[36:37], 0xd8
	s_lshl_b32 s10, s76, 3
	s_lshl_b32 s1, s17, 6
	v_and_b32_e32 v184, 31, v0
	s_waitcnt vmcnt(0)
	v_lshlrev_b32_e32 v4, 4, v0
	s_waitcnt lgkmcnt(0)
	s_add_u32 s46, s40, 0xac20000
	s_addc_u32 s47, s41, 0
	s_add_u32 s48, s40, 0xb060000
	s_addc_u32 s49, s41, 0
	s_add_u32 s42, s40, 0xb4a0000
	s_addc_u32 s43, s41, 0
	s_add_i32 s10, s17, s10
	s_ashr_i32 s11, s10, 31
	s_lshl_b64 s[38:39], s[10:11], 2
	s_load_dwordx2 s[10:11], s[36:37], 0x90
	s_load_dwordx4 s[52:55], s[36:37], 0x98
	v_and_b32_e32 v6, 0xc0, v4
	v_lshlrev_b32_e32 v7, 1, v0
	v_and_b32_e32 v7, 32, v7
	s_waitcnt lgkmcnt(0)
	s_add_u32 s10, s10, s38
	s_addc_u32 s11, s11, s39
	global_load_dword v2, v1, s[10:11]
	s_lshl_b32 s10, s17, 8
	s_add_i32 s15, s10, 0
	s_lshl_b32 s26, s76, 10
	s_add_i32 s15, s15, 0x20000
	s_lshl_b64 s[10:11], s[26:27], 2
	s_add_u32 s56, s52, s10
	s_addc_u32 s57, s53, s11
	s_add_u32 s54, s54, s10
	s_addc_u32 s55, s55, s11
	s_lshl_b32 s60, s17, 7
	s_ashr_i32 s61, s60, 31
	s_lshl_b64 s[52:53], s[60:61], 1
	s_add_u32 s10, s40, s52
	s_addc_u32 s11, s41, s53
	s_add_u32 s50, s10, 0x9b20000
	s_addc_u32 s51, s11, 0
	s_lshl_b32 s10, s17, 12
	s_and_b32 s10, s10, 0xffffc000
	s_add_i32 s11, s10, 0
	v_lshl_add_u32 v188, v184, 8, s11
	s_add_i32 s11, 0, 0x8000
	v_add_u32_e32 v6, s11, v6
	v_ashrrev_i32_e32 v185, 5, v0
	v_mov_b32_e32 v163, v1
	s_mulk_i32 s17, 0x2200
	v_lshlrev_b32_e32 v187, 4, v185
	v_cmp_gt_u32_e64 s[36:37], 32, v0
	s_mov_b64 s[28:29], 0xd6a0000
	s_add_i32 s17, s17, 0
	v_ashrrev_i32_e32 v194, 4, v0
	v_lshl_add_u32 v193, v184, 1, s17
	v_lshlrev_b32_e32 v189, 2, v185
	v_lshlrev_b32_e32 v5, 2, v184
	v_readlane_b32 s23, v255, 7
	s_add_i32 s11, s60, 0
	s_add_i32 s11, s11, 0x20c00
	v_add_u32_e32 v190, s15, v5
	v_add_u32_e32 v209, s15, v187
	s_movk_i32 s15, 0x440
	v_cmp_eq_u32_e64 s[38:39], 0, v184
	s_waitcnt vmcnt(0)
	v_mul_f32_e32 v186, 0x3fb8aa3b, v2
	v_lshlrev_b32_e32 v2, 3, v0
	v_and_b32_e32 v3, 24, v2
	v_and_b32_e32 v2, 0x100, v2
	v_add3_u32 v3, v6, v3, v7
	v_add3_u32 v191, v3, v2, s10
	v_and_b32_e32 v2, 7, v0
	v_lshlrev_b32_e32 v162, 4, v2
	v_and_b32_e32 v6, -8, v0
	v_lshlrev_b32_e32 v192, 2, v2
	v_lshl_add_u64 v[2:3], s[40:41], 0, v[162:163]
	v_cmp_gt_i32_e64 s[40:41], 8, v0
	v_and_b32_e32 v0, 0xf0, v4
	v_lshl_add_u64 v[164:165], v[2:3], 0, s[28:29]
	v_add_u32_e32 v196, s17, v0
	s_movk_i32 s17, 0x70
	v_add_u32_e32 v3, 32, v187
	v_bitop3_b32 v202, v3, v4, s17 bitop3:0x78
	v_add_u32_e32 v3, 64, v187
	v_bitop3_b32 v203, v3, v4, s17 bitop3:0x78
	v_add_u32_e32 v3, 0x60, v187
	v_bitop3_b32 v204, v3, v4, s17 bitop3:0x78
	v_add_u32_e32 v3, 0x80, v187
	v_bitop3_b32 v205, v3, v4, s17 bitop3:0x78
	v_add_u32_e32 v3, 0xa0, v187
	v_bitop3_b32 v206, v3, v4, s17 bitop3:0x78
	v_add_u32_e32 v3, 0xc0, v187
	v_bitop3_b32 v207, v3, v4, s17 bitop3:0x78
	v_add_u32_e32 v3, 0xe0, v187
	v_or_b32_e32 v2, s60, v184
	v_bitop3_b32 v200, v187, v4, s17 bitop3:0x78
	v_bitop3_b32 v208, v3, v4, s17 bitop3:0x78
	v_add_u32_e32 v4, s1, v6
	s_mov_b32 s17, 0x8800
	v_add_u32_e32 v6, 0x200, v4
	v_ashrrev_i32_e32 v3, 31, v2
	s_add_i32 s10, s23, s60
	v_add_u32_e32 v163, s23, v5
	s_movk_i32 s23, 0x110
	v_mad_i64_i32 v[166:167], s[28:29], v4, s17, 0
	v_mad_i64_i32 v[168:169], s[28:29], v6, s17, 0
	v_lshl_add_u64 v[180:181], v[2:3], 2, s[54:55]
	v_or_b32_e32 v3, 1, v189
	v_mul_lo_u32 v198, v194, s23
	v_ashrrev_i32_e32 v5, 31, v4
	v_mul_lo_u32 v210, v3, s23
	s_add_u32 s28, s42, s52
	v_ashrrev_i32_e32 v7, 31, v6
	v_lshl_add_u64 v[174:175], v[4:5], 2, s[56:57]
	v_lshl_add_u64 v[176:177], v[4:5], 1, s[42:43]
	v_mul_lo_u32 v2, v185, s15
	v_add_u32_e32 v3, 0x990, v210
	v_add_u32_e32 v4, 0x440, v198
	s_addc_u32 s29, s43, s53
	v_lshl_add_u64 v[178:179], v[6:7], 1, s[42:43]
	v_lshl_add_u64 v[182:183], s[28:29], 0, v[0:1]
	v_add_u32_e32 v211, v193, v2
	v_add_u32_e32 v212, v193, v3
	v_add_u32_e32 v213, v196, v4
	v_mbcnt_lo_u32_b32 v66, -1, 0
	v_mbcnt_hi_u32_b32 v66, -1, v66
	v_add_u32_e32 v67, s1, v66
	v_ashrrev_i32_e32 v68, 4, v67
	v_and_b32_e32 v70, 0xfffff0, v68
	v_lshlrev_b32_e32 v71, 1, v68
	v_lshlrev_b32_e32 v66, 3, v66
	v_and_or_b32 v70, v71, 8, v70
	v_and_b32_e32 v69, 0x78, v66
	v_lshrrev_b32_e32 v70, 1, v70
	v_bfe_u32 v66, v66, 5, 2
	v_lshrrev_b32_e32 v71, 1, v68
	v_or_b32_e32 v66, v70, v66
	v_and_b32_e32 v70, 3, v68
	v_lshlrev_b32_e32 v69, 1, v69
	v_and_or_b32 v70, v71, 4, v70
	v_and_b32_e32 v71, 48, v69
	v_lshlrev_b32_e32 v68, 8, v68
	v_and_b32_e32 v67, 0x70, v67
	v_lshl_or_b32 v70, v70, 6, v71
	v_bitop3_b32 v67, v69, v68, v67 bitop3:0xde
	v_lshl_or_b32 v66, v66, 9, v70
	v_mov_b32_e32 v233, v67
	v_mov_b32_e32 v234, v66
	v_mbcnt_lo_u32_b32 v236, -1, 0
	v_mbcnt_hi_u32_b32 v236, -1, v236
	v_add_u32_e32 v235, s1, v236
	v_ashrrev_i32_e32 v235, 4, v235
	v_lshlrev_b32_e32 v236, 4, v236
	v_and_b32_e32 v236, 0xf0, v236
	s_add_i32 s15, s2, s3
	s_cmp_lt_i32 s15, s0
	s_cselect_b32 s15, s15, s2
	s_branch .LBB0_789
; #define LAS __attribute__((address_space(3)))
; __device__ __forceinline__ unsigned f2bf(float f) { unsigned u = __builtin_bit_cast(unsigned, f); return (u + 0x7fffu + ((u >> 16) & 1u)) >> 16; }
; __device__ __forceinline__ int crow(int r, int hi) { return (r & 3) + 8 * (r >> 2) + 4 * hi; }
; __device__ __forceinline__ void attn_mfma(LAS unsigned char* lds, int layer, int G, const int wave_s) {
;     ...
;     for (int unit = blockIdx.x; unit < nunits; unit += G) {
;     ...
;         if (hi == 0) al_l[r32] = ra; asm volatile("s_waitcnt lgkmcnt(0)" ::: "memory");
;         { LAS unsigned char* ost = lds + AT_OST + wave * (32 * 272);
;           float gc[4];
; #pragma unroll
;           for (int d = 0; d < 4; ++d) gc[d] = gat[h * HD + 32 * d + r32];
; #pragma unroll
;           for (int r = 0; r < 16; ++r) { const int q = crow(r, hi); const float rq = al_l[q];
; #pragma unroll
;               for (int d = 0; d < 4; ++d) *(LAS bf16_t*)(ost + q * 272 + (32 * d + r32) * 2) = (bf16_t)f2bf(o[d][r] * rq * gc[d]); }
;           asm volatile("s_waitcnt lgkmcnt(0)" ::: "memory");
; #pragma unroll
;           for (int k = 0; k < 8; ++k) { const int q = k * 4 + (lane >> 4), ch = lane & 15;
;               const u32x4 v = *(const LAS u32x4*)(ost + q * 272 + ch * 16);
;               *(u32x4*)(YM + (size_t)(rowbase + q) * D + HY + h * HD + ch * 8) = v; } }
.LBB0_788:
	s_or_b64 exec, exec, s[54:55]
	s_waitcnt lgkmcnt(0)
	global_load_dword v8, v[180:181], off
	global_load_dword v7, v[180:181], off offset:128
	global_load_dword v6, v[180:181], off offset:256
	global_load_dword v0, v[180:181], off offset:384
	ds_read_b128 v[2:5], v209
	s_sub_i32 s4, s15, s3
	s_lshl_b32 s5, s3, 1
	s_add_i32 s5, s15, s5
	s_cmp_ge_i32 s15, s3
	s_cselect_b32 s15, s4, s5
	s_cmp_lt_i32 s15, s0
	s_waitcnt lgkmcnt(0)
	v_mul_f32_e32 v9, v140, v2
	s_waitcnt vmcnt(3)
	v_mul_f32_e32 v9, v8, v9
	v_bfe_u32 v10, v9, 16, 1
	v_add3_u32 v9, v9, v10, s66
	ds_write_b16_d16_hi v211, v9
	v_mul_f32_e32 v9, v130, v2
	s_waitcnt vmcnt(2)
	v_mul_f32_e32 v9, v7, v9
	v_bfe_u32 v10, v9, 16, 1
	v_add3_u32 v9, v9, v10, s66
	ds_write_b16_d16_hi v211, v9 offset:64
	v_mul_f32_e32 v9, v128, v2
	s_waitcnt vmcnt(1)
	v_mul_f32_e32 v9, v6, v9
	v_bfe_u32 v10, v9, 16, 1
	v_mul_f32_e32 v2, v126, v2
	v_add3_u32 v9, v9, v10, s66
	s_waitcnt vmcnt(0)
	v_mul_f32_e32 v2, v0, v2
	ds_write_b16_d16_hi v211, v9 offset:128
	v_bfe_u32 v9, v2, 16, 1
	v_add3_u32 v2, v2, v9, s66
	ds_write_b16_d16_hi v211, v2 offset:192
	v_mul_f32_e32 v2, v141, v3
	v_mul_f32_e32 v2, v8, v2
	v_bfe_u32 v9, v2, 16, 1
	v_add3_u32 v2, v2, v9, s66
	v_add_u32_e32 v9, v193, v210
	ds_write_b16_d16_hi v9, v2
	v_mul_f32_e32 v2, v131, v3
	v_mul_f32_e32 v2, v7, v2
	v_bfe_u32 v10, v2, 16, 1
	v_add3_u32 v2, v2, v10, s66
	ds_write_b16_d16_hi v9, v2 offset:64
	v_mul_f32_e32 v2, v129, v3
	v_mul_f32_e32 v2, v6, v2
	v_bfe_u32 v10, v2, 16, 1
	v_add3_u32 v2, v2, v10, s66
	ds_write_b16_d16_hi v9, v2 offset:128
	v_mul_f32_e32 v2, v127, v3
	v_mul_f32_e32 v2, v0, v2
	v_bfe_u32 v3, v2, 16, 1
	v_add3_u32 v2, v2, v3, s66
	ds_write_b16_d16_hi v9, v2 offset:192
	v_mul_f32_e32 v2, v138, v4
	v_mul_f32_e32 v2, v8, v2
	v_bfe_u32 v3, v2, 16, 1
	v_add3_u32 v2, v2, v3, s66
	ds_write_b16_d16_hi v9, v2 offset:272
	v_mul_f32_e32 v2, v134, v4
	v_mul_f32_e32 v2, v7, v2
	v_bfe_u32 v3, v2, 16, 1
	v_add3_u32 v2, v2, v3, s66
	ds_write_b16_d16_hi v9, v2 offset:336
	v_mul_f32_e32 v2, v136, v4
	v_mul_f32_e32 v2, v6, v2
	v_bfe_u32 v3, v2, 16, 1
	v_add3_u32 v2, v2, v3, s66
	ds_write_b16_d16_hi v9, v2 offset:400
	v_mul_f32_e32 v2, v132, v4
	v_mul_f32_e32 v2, v0, v2
	v_bfe_u32 v3, v2, 16, 1
	v_add3_u32 v2, v2, v3, s66
	ds_write_b16_d16_hi v9, v2 offset:464
	v_mul_f32_e32 v2, v139, v5
	v_mul_f32_e32 v2, v8, v2
	v_bfe_u32 v3, v2, 16, 1
	v_add3_u32 v2, v2, v3, s66
	ds_write_b16_d16_hi v9, v2 offset:544
	v_mul_f32_e32 v2, v135, v5
	v_mul_f32_e32 v2, v7, v2
	v_bfe_u32 v3, v2, 16, 1
	v_add3_u32 v2, v2, v3, s66
	ds_write_b16_d16_hi v9, v2 offset:608
	v_mul_f32_e32 v2, v137, v5
	v_mul_f32_e32 v2, v6, v2
	v_bfe_u32 v3, v2, 16, 1
	v_add3_u32 v2, v2, v3, s66
	ds_write_b16_d16_hi v9, v2 offset:672
	v_mul_f32_e32 v2, v133, v5
	v_mul_f32_e32 v2, v0, v2
	v_bfe_u32 v3, v2, 16, 1
	v_add3_u32 v2, v2, v3, s66
	ds_write_b16_d16_hi v9, v2 offset:736
	ds_read_b128 v[2:5], v209 offset:32
	s_waitcnt lgkmcnt(0)
	v_mul_f32_e32 v10, v100, v2
	v_mul_f32_e32 v10, v8, v10
	v_bfe_u32 v11, v10, 16, 1
	v_add3_u32 v10, v10, v11, s66
	ds_write_b16_d16_hi v9, v10 offset:1904
	v_mul_f32_e32 v10, v96, v2
	v_mul_f32_e32 v10, v7, v10
	v_bfe_u32 v11, v10, 16, 1
	v_add3_u32 v10, v10, v11, s66
	ds_write_b16_d16_hi v9, v10 offset:1968
	v_mul_f32_e32 v10, v98, v2
	v_mul_f32_e32 v10, v6, v10
	v_bfe_u32 v11, v10, 16, 1
	v_mul_f32_e32 v2, v94, v2
	v_add3_u32 v10, v10, v11, s66
	v_mul_f32_e32 v2, v0, v2
	ds_write_b16_d16_hi v9, v10 offset:2032
	v_bfe_u32 v10, v2, 16, 1
	v_add3_u32 v2, v2, v10, s66
	ds_write_b16_d16_hi v9, v2 offset:2096
	v_mul_f32_e32 v2, v101, v3
	v_mul_f32_e32 v2, v8, v2
	v_bfe_u32 v10, v2, 16, 1
	v_add3_u32 v2, v2, v10, s66
	ds_write_b16_d16_hi v9, v2 offset:2176
	v_mul_f32_e32 v2, v97, v3
	v_mul_f32_e32 v2, v7, v2
	v_bfe_u32 v10, v2, 16, 1
	v_add3_u32 v2, v2, v10, s66
	ds_write_b16_d16_hi v9, v2 offset:2240
	v_mul_f32_e32 v2, v99, v3
	v_mul_f32_e32 v2, v6, v2
	v_bfe_u32 v10, v2, 16, 1
	v_add3_u32 v2, v2, v10, s66
	ds_write_b16_d16_hi v9, v2 offset:2304
	v_mul_f32_e32 v2, v95, v3
	v_mul_f32_e32 v2, v0, v2
	v_bfe_u32 v3, v2, 16, 1
	v_add3_u32 v2, v2, v3, s66
	ds_write_b16_d16_hi v9, v2 offset:2368
	v_mul_f32_e32 v2, v108, v4
	v_mul_f32_e32 v2, v8, v2
	v_bfe_u32 v3, v2, 16, 1
	v_add3_u32 v2, v2, v3, s66
	ds_write_b16_d16_hi v9, v2 offset:2448
	v_mul_f32_e32 v2, v104, v4
	v_mul_f32_e32 v2, v7, v2
	v_bfe_u32 v3, v2, 16, 1
	v_add3_u32 v2, v2, v3, s66
	ds_write_b16_d16_hi v212, v2 offset:64
	v_mul_f32_e32 v2, v106, v4
	v_mul_f32_e32 v2, v6, v2
	v_bfe_u32 v3, v2, 16, 1
	v_add3_u32 v2, v2, v3, s66
	ds_write_b16_d16_hi v212, v2 offset:128
	v_mul_f32_e32 v2, v102, v4
	v_mul_f32_e32 v2, v0, v2
	v_bfe_u32 v3, v2, 16, 1
	v_add3_u32 v2, v2, v3, s66
	ds_write_b16_d16_hi v212, v2 offset:192
	v_mul_f32_e32 v2, v109, v5
	v_mul_f32_e32 v2, v8, v2
	v_bfe_u32 v3, v2, 16, 1
	v_add3_u32 v2, v2, v3, s66
	ds_write_b16_d16_hi v212, v2 offset:272
	v_mul_f32_e32 v2, v105, v5
	v_mul_f32_e32 v2, v7, v2
	v_bfe_u32 v3, v2, 16, 1
	v_add3_u32 v2, v2, v3, s66
	ds_write_b16_d16_hi v212, v2 offset:336
	v_mul_f32_e32 v2, v107, v5
	v_mul_f32_e32 v2, v6, v2
	v_bfe_u32 v3, v2, 16, 1
	v_add3_u32 v2, v2, v3, s66
	ds_write_b16_d16_hi v212, v2 offset:400
	v_mul_f32_e32 v2, v103, v5
	v_mul_f32_e32 v2, v0, v2
	v_bfe_u32 v3, v2, 16, 1
	v_add3_u32 v2, v2, v3, s66
	ds_write_b16_d16_hi v212, v2 offset:464
	ds_read_b128 v[2:5], v209 offset:64
	s_waitcnt lgkmcnt(0)
; #define LAS __attribute__((address_space(3)))
; __device__ __forceinline__ unsigned f2bf(float f) { unsigned u = __builtin_bit_cast(unsigned, f); return (u + 0x7fffu + ((u >> 16) & 1u)) >> 16; }
; __device__ __forceinline__ int crow(int r, int hi) { return (r & 3) + 8 * (r >> 2) + 4 * hi; }
; __device__ __forceinline__ void attn_mfma(LAS unsigned char* lds, int layer, int G, const int wave_s) {
;     ...
;         { LAS unsigned char* ost = lds + AT_OST + wave * (32 * 272);
;           float gc[4];
; #pragma unroll
;           for (int d = 0; d < 4; ++d) gc[d] = gat[h * HD + 32 * d + r32];
; #pragma unroll
;           for (int r = 0; r < 16; ++r) { const int q = crow(r, hi); const float rq = al_l[q];
; #pragma unroll
;               for (int d = 0; d < 4; ++d) *(LAS bf16_t*)(ost + q * 272 + (32 * d + r32) * 2) = (bf16_t)f2bf(o[d][r] * rq * gc[d]); }
;           asm volatile("s_waitcnt lgkmcnt(0)" ::: "memory");
; #pragma unroll
;           for (int k = 0; k < 8; ++k) { const int q = k * 4 + (lane >> 4), ch = lane & 15;
;               const u32x4 v = *(const LAS u32x4*)(ost + q * 272 + ch * 16);
;               *(u32x4*)(YM + (size_t)(rowbase + q) * D + HY + h * HD + ch * 8) = v; } }
	v_mul_f32_e32 v9, v124, v2
	v_mul_f32_e32 v9, v8, v9
	v_bfe_u32 v10, v9, 16, 1
	v_add3_u32 v9, v9, v10, s66
	ds_write_b16_d16_hi v212, v9 offset:1632
	v_mul_f32_e32 v9, v122, v2
	v_mul_f32_e32 v9, v7, v9
	v_bfe_u32 v10, v9, 16, 1
	v_add3_u32 v9, v9, v10, s66
	ds_write_b16_d16_hi v212, v9 offset:1696
	v_mul_f32_e32 v9, v120, v2
	v_mul_f32_e32 v9, v6, v9
	v_bfe_u32 v10, v9, 16, 1
	v_mul_f32_e32 v2, v118, v2
	v_add3_u32 v9, v9, v10, s66
	v_mul_f32_e32 v2, v0, v2
	ds_write_b16_d16_hi v212, v9 offset:1760
	v_bfe_u32 v9, v2, 16, 1
	v_add3_u32 v2, v2, v9, s66
	ds_write_b16_d16_hi v212, v2 offset:1824
	v_mul_f32_e32 v2, v125, v3
	v_mul_f32_e32 v2, v8, v2
	v_bfe_u32 v9, v2, 16, 1
	v_add3_u32 v2, v2, v9, s66
	ds_write_b16_d16_hi v212, v2 offset:1904
	v_mul_f32_e32 v2, v123, v3
	v_mul_f32_e32 v2, v7, v2
	v_bfe_u32 v9, v2, 16, 1
	v_add3_u32 v2, v2, v9, s66
	ds_write_b16_d16_hi v212, v2 offset:1968
	v_mul_f32_e32 v2, v121, v3
	v_mul_f32_e32 v2, v6, v2
	v_bfe_u32 v9, v2, 16, 1
	v_add3_u32 v2, v2, v9, s66
	ds_write_b16_d16_hi v212, v2 offset:2032
	v_mul_f32_e32 v2, v119, v3
	v_mul_f32_e32 v2, v0, v2
	v_bfe_u32 v3, v2, 16, 1
	v_add3_u32 v2, v2, v3, s66
	ds_write_b16_d16_hi v212, v2 offset:2096
	v_mul_f32_e32 v2, v116, v4
	v_mul_f32_e32 v2, v8, v2
	v_bfe_u32 v3, v2, 16, 1
	v_add3_u32 v2, v2, v3, s66
	ds_write_b16_d16_hi v212, v2 offset:2176
	v_mul_f32_e32 v2, v114, v4
	v_mul_f32_e32 v2, v7, v2
	v_bfe_u32 v3, v2, 16, 1
	v_add3_u32 v2, v2, v3, s66
	ds_write_b16_d16_hi v212, v2 offset:2240
	v_mul_f32_e32 v2, v112, v4
	v_mul_f32_e32 v2, v6, v2
	v_bfe_u32 v3, v2, 16, 1
	v_add3_u32 v2, v2, v3, s66
	ds_write_b16_d16_hi v212, v2 offset:2304
	v_mul_f32_e32 v2, v110, v4
	v_mul_f32_e32 v2, v0, v2
	v_bfe_u32 v3, v2, 16, 1
	v_add3_u32 v2, v2, v3, s66
	ds_write_b16_d16_hi v212, v2 offset:2368
	v_mul_f32_e32 v2, v117, v5
	v_mul_f32_e32 v2, v8, v2
	v_bfe_u32 v3, v2, 16, 1
	v_add3_u32 v2, v2, v3, s66
	ds_write_b16_d16_hi v212, v2 offset:2448
	v_mul_f32_e32 v2, v115, v5
	v_mul_f32_e32 v2, v7, v2
	v_bfe_u32 v3, v2, 16, 1
	v_add3_u32 v2, v2, v3, s66
	ds_write_b16_d16_hi v212, v2 offset:2512
	v_mul_f32_e32 v2, v113, v5
	v_mul_f32_e32 v2, v6, v2
	v_bfe_u32 v3, v2, 16, 1
	v_add3_u32 v2, v2, v3, s66
	ds_write_b16_d16_hi v212, v2 offset:2576
	v_mul_f32_e32 v2, v111, v5
	v_mul_f32_e32 v2, v0, v2
	v_bfe_u32 v3, v2, 16, 1
	v_add3_u32 v2, v2, v3, s66
	ds_write_b16_d16_hi v212, v2 offset:2640
	ds_read_b128 v[2:5], v209 offset:96
	s_waitcnt lgkmcnt(0)
	v_mul_f32_e32 v9, v84, v2
	v_mul_f32_e32 v9, v8, v9
	v_bfe_u32 v10, v9, 16, 1
	v_add3_u32 v9, v9, v10, s66
	ds_write_b16_d16_hi v212, v9 offset:3808
	v_mul_f32_e32 v9, v80, v2
	v_mul_f32_e32 v9, v7, v9
	v_bfe_u32 v10, v9, 16, 1
	v_add3_u32 v9, v9, v10, s66
	ds_write_b16_d16_hi v212, v9 offset:3872
	v_mul_f32_e32 v9, v82, v2
	v_mul_f32_e32 v9, v6, v9
	v_bfe_u32 v10, v9, 16, 1
	v_mul_f32_e32 v2, v78, v2
	v_add3_u32 v9, v9, v10, s66
	v_mul_f32_e32 v2, v0, v2
	ds_write_b16_d16_hi v212, v9 offset:3936
	v_bfe_u32 v9, v2, 16, 1
	v_add3_u32 v2, v2, v9, s66
	ds_write_b16_d16_hi v212, v2 offset:4000
	v_mul_f32_e32 v2, v85, v3
	v_mul_f32_e32 v2, v8, v2
	v_bfe_u32 v9, v2, 16, 1
	v_add3_u32 v2, v2, v9, s66
	ds_write_b16_d16_hi v212, v2 offset:4080
	v_mul_f32_e32 v2, v81, v3
	v_mul_f32_e32 v2, v7, v2
	v_bfe_u32 v9, v2, 16, 1
	v_add3_u32 v2, v2, v9, s66
	ds_write_b16_d16_hi v212, v2 offset:4144
	v_mul_f32_e32 v2, v83, v3
	v_mul_f32_e32 v2, v6, v2
	v_bfe_u32 v9, v2, 16, 1
	v_add3_u32 v2, v2, v9, s66
	ds_write_b16_d16_hi v212, v2 offset:4208
	v_mul_f32_e32 v2, v79, v3
	v_mul_f32_e32 v2, v0, v2
	v_bfe_u32 v3, v2, 16, 1
	v_add3_u32 v2, v2, v3, s66
	ds_write_b16_d16_hi v212, v2 offset:4272
	v_mul_f32_e32 v2, v92, v4
	v_mul_f32_e32 v2, v8, v2
	v_bfe_u32 v3, v2, 16, 1
	v_add3_u32 v2, v2, v3, s66
	ds_write_b16_d16_hi v212, v2 offset:4352
	v_mul_f32_e32 v2, v88, v4
	v_mul_f32_e32 v2, v7, v2
	v_bfe_u32 v3, v2, 16, 1
	v_add3_u32 v2, v2, v3, s66
	ds_write_b16_d16_hi v212, v2 offset:4416
	v_mul_f32_e32 v2, v90, v4
	v_mul_f32_e32 v2, v6, v2
	v_bfe_u32 v3, v2, 16, 1
	v_add3_u32 v2, v2, v3, s66
	ds_write_b16_d16_hi v212, v2 offset:4480
	v_mul_f32_e32 v2, v86, v4
	v_mul_f32_e32 v2, v0, v2
	v_bfe_u32 v3, v2, 16, 1
	v_add3_u32 v2, v2, v3, s66
	ds_write_b16_d16_hi v212, v2 offset:4544
	v_mul_f32_e32 v2, v93, v5
	v_mul_f32_e32 v2, v8, v2
	v_bfe_u32 v3, v2, 16, 1
	v_add3_u32 v2, v2, v3, s66
	ds_write_b16_d16_hi v212, v2 offset:4624
	v_mul_f32_e32 v2, v89, v5
	v_mul_f32_e32 v2, v7, v2
	v_bfe_u32 v3, v2, 16, 1
	v_add3_u32 v2, v2, v3, s66
	ds_write_b16_d16_hi v212, v2 offset:4688
	v_mul_f32_e32 v2, v91, v5
	v_mul_f32_e32 v2, v6, v2
	v_bfe_u32 v3, v2, 16, 1
	v_add3_u32 v2, v2, v3, s66
	ds_write_b16_d16_hi v212, v2 offset:4752
	v_mul_f32_e32 v2, v87, v5
	v_mul_f32_e32 v0, v0, v2
	v_bfe_u32 v2, v0, 16, 1
	v_add3_u32 v0, v0, v2, s66
	ds_write_b16_d16_hi v212, v0 offset:4816
	s_waitcnt lgkmcnt(0)
	v_add_u32_e32 v0, v196, v198
	ds_read_b128 v[2:5], v0
	v_add_u32_e32 v6, s52, v194
	v_ashrrev_i32_e32 v7, 31, v6
	v_lshlrev_b64 v[8:9], 12, v[6:7]
	v_lshl_add_u64 v[8:9], v[182:183], 0, v[8:9]
	s_waitcnt lgkmcnt(0)
	global_store_dwordx4 v[8:9], v[2:5], off offset:2048
	ds_read_b128 v[2:5], v213
	v_add_u32_e32 v0, 4, v194
	v_add_u32_e32 v8, s52, v0
	v_ashrrev_i32_e32 v9, 31, v8
	v_lshlrev_b64 v[8:9], 12, v[8:9]
	v_lshl_add_u64 v[8:9], v[182:183], 0, v[8:9]
	s_waitcnt lgkmcnt(0)
	global_store_dwordx4 v[8:9], v[2:5], off offset:2048
	ds_read_b128 v[2:5], v213 offset:1088
	v_add_u32_e32 v8, 8, v6
	v_ashrrev_i32_e32 v9, 31, v8
	v_lshlrev_b64 v[8:9], 12, v[8:9]
	v_lshl_add_u64 v[8:9], v[182:183], 0, v[8:9]
	s_waitcnt lgkmcnt(0)
	global_store_dwordx4 v[8:9], v[2:5], off offset:2048
	ds_read_b128 v[2:5], v213 offset:2176
	v_add_u32_e32 v8, 12, v6
	v_ashrrev_i32_e32 v9, 31, v8
	v_lshlrev_b64 v[8:9], 12, v[8:9]
	v_lshl_add_u64 v[8:9], v[182:183], 0, v[8:9]
	s_waitcnt lgkmcnt(0)
	global_store_dwordx4 v[8:9], v[2:5], off offset:2048
	ds_read_b128 v[2:5], v213 offset:3264
	v_add_u32_e32 v8, 16, v6
	v_ashrrev_i32_e32 v9, 31, v8
	v_lshlrev_b64 v[8:9], 12, v[8:9]
	v_lshl_add_u64 v[8:9], v[182:183], 0, v[8:9]
	s_waitcnt lgkmcnt(0)
	global_store_dwordx4 v[8:9], v[2:5], off offset:2048
	ds_read_b128 v[2:5], v213 offset:4352
	v_add_u32_e32 v8, 20, v6
	v_ashrrev_i32_e32 v9, 31, v8
	v_lshlrev_b64 v[8:9], 12, v[8:9]
	v_lshl_add_u64 v[8:9], v[182:183], 0, v[8:9]
	s_waitcnt lgkmcnt(0)
	global_store_dwordx4 v[8:9], v[2:5], off offset:2048
	ds_read_b128 v[2:5], v213 offset:5440
	v_add_u32_e32 v8, 24, v6
	v_ashrrev_i32_e32 v9, 31, v8
	v_lshlrev_b64 v[8:9], 12, v[8:9]
	v_lshl_add_u64 v[8:9], v[182:183], 0, v[8:9]
	s_waitcnt lgkmcnt(0)
	global_store_dwordx4 v[8:9], v[2:5], off offset:2048
	ds_read_b128 v[2:5], v213 offset:6528
	v_add_u32_e32 v6, 28, v6
	v_ashrrev_i32_e32 v7, 31, v6
	v_lshlrev_b64 v[6:7], 12, v[6:7]
	v_lshl_add_u64 v[6:7], v[182:183], 0, v[6:7]
	s_waitcnt lgkmcnt(0)
	global_store_dwordx4 v[6:7], v[2:5], off offset:2048
	s_cbranch_scc0 .LBB0_826
